# final RMSNorm pass: all 16 row loads of an iteration issued up front into free registers with counted vmcnt waits (was 2 loads per serialized round trip)
# speedup vs baseline: 1.0248x; 1.0238x over previous
.LBB0_582:
	s_nop 0
	v_lshl_add_u64 v[32:33], v[22:23], 0, s[10:11]
	v_add_co_u32_e32 v28, vcc, s16, v32
	v_mov_b32_e32 v16, s14
	s_nop 0
	v_addc_co_u32_e32 v29, vcc, 0, v33, vcc
	v_add_co_u32_e32 v64, vcc, s18, v32
	ds_read_b128 v[48:51], v16
	ds_read_b128 v[16:19], v16 offset:16
	v_addc_co_u32_e32 v65, vcc, 0, v33, vcc
	global_load_dwordx4 v[80:83], v[64:65], off offset:-4096
	global_load_dwordx4 v[84:87], v[28:29], off offset:1024
	v_lshl_add_u64 v[24:25], v[20:21], 0, s[12:13]
	v_add_co_u32_e64 v34, s[0:1], s17, v24
	s_waitcnt lgkmcnt(1)
	v_fmamk_f32 v47, v50, 0x3a800000, v46
	v_addc_co_u32_e64 v35, s[0:1], 0, v25, s[0:1]
	v_add_co_u32_e64 v30, s[0:1], s19, v24
	s_waitcnt lgkmcnt(0)
	v_fmamk_f32 v16, v16, 0x3a800000, v46
	v_addc_co_u32_e64 v31, s[0:1], 0, v25, s[0:1]
	v_add_co_u32_e64 v40, s[0:1], s20, v24
	v_fmamk_f32 v17, v17, 0x3a800000, v46
	s_nop 0
	v_addc_co_u32_e64 v41, s[0:1], 0, v25, s[0:1]
	v_add_co_u32_e64 v36, s[0:1], s22, v24
	v_mul_f32_e32 v61, 0x4b800000, v16
	s_nop 0
	v_addc_co_u32_e64 v37, s[0:1], 0, v25, s[0:1]
	v_add_co_u32_e64 v42, s[0:1], s21, v32
	v_cmp_gt_f32_e64 s[4:5], s15, v16
	s_nop 0
	v_addc_co_u32_e64 v43, s[0:1], 0, v33, s[0:1]
	v_add_co_u32_e64 v26, s[0:1], s24, v32
	v_fmamk_f32 v32, v48, 0x3a800000, v46
	s_nop 0
	v_addc_co_u32_e64 v27, s[0:1], 0, v33, s[0:1]
	v_add_co_u32_e64 v44, s[0:1], s23, v24
	v_fmamk_f32 v33, v49, 0x3a800000, v46
	s_nop 0
	v_addc_co_u32_e64 v45, s[0:1], 0, v25, s[0:1]
	v_add_co_u32_e64 v38, s[0:1], s25, v24
	v_fmamk_f32 v48, v51, 0x3a800000, v46
	s_nop 0
	v_addc_co_u32_e64 v39, s[0:1], 0, v25, s[0:1]
	v_mul_f32_e32 v49, 0x4b800000, v32
	v_mul_f32_e32 v50, 0x4b800000, v33
	v_cmp_gt_f32_e32 vcc, s15, v33
	v_mul_f32_e32 v51, 0x4b800000, v47
	v_cmp_gt_f32_e64 s[0:1], s15, v47
	v_mul_f32_e32 v60, 0x4b800000, v48
	v_cmp_gt_f32_e64 s[2:3], s15, v48
	v_cmp_gt_f32_e64 s[8:9], s15, v32
	v_mul_f32_e32 v62, 0x4b800000, v17
	v_cmp_gt_f32_e64 s[6:7], s15, v17
	v_cndmask_b32_e64 v32, v32, v49, s[8:9]
	v_cndmask_b32_e32 v33, v33, v50, vcc
	v_cndmask_b32_e64 v47, v47, v51, s[0:1]
	v_cndmask_b32_e64 v48, v48, v60, s[2:3]
	v_cndmask_b32_e64 v16, v16, v61, s[4:5]
	v_cndmask_b32_e64 v17, v17, v62, s[6:7]
	v_rsq_f32_e32 v32, v32
	v_rsq_f32_e32 v33, v33
	v_rsq_f32_e32 v47, v47
	v_rsq_f32_e32 v48, v48
	v_rsq_f32_e32 v49, v16
	v_rsq_f32_e32 v17, v17
	v_mul_f32_e32 v16, 0x45800000, v32
	v_mul_f32_e32 v50, 0x45800000, v33
	v_mul_f32_e32 v51, 0x45800000, v47
	v_mul_f32_e32 v60, 0x45800000, v48
	v_mul_f32_e32 v61, 0x45800000, v49
	v_mul_f32_e32 v62, 0x45800000, v17
	v_cndmask_b32_e64 v16, v32, v16, s[8:9]
	v_cndmask_b32_e32 v32, v33, v50, vcc
	v_cndmask_b32_e64 v66, v47, v51, s[0:1]
	v_cndmask_b32_e64 v68, v48, v60, s[2:3]
	v_cndmask_b32_e64 v70, v49, v61, s[4:5]
	v_cndmask_b32_e64 v72, v17, v62, s[6:7]
	s_add_i32 s14, s14, 32
	s_add_u32 s12, s12, 0x8000
	s_addc_u32 s13, s13, 0
	global_load_dwordx4 v[88:91], v[28:29], off offset:2048
	global_load_dwordx4 v[92:95], v[28:29], off offset:3072
	global_load_dwordx4 v[96:99], v[64:65], off
	global_load_dwordx4 v[100:103], v[64:65], off offset:1024
	global_load_dwordx4 v[104:107], v[64:65], off offset:2048
	global_load_dwordx4 v[108:111], v[64:65], off offset:3072
	global_load_dwordx4 v[112:115], v[26:27], off offset:-4096
	global_load_dwordx4 v[116:119], v[42:43], off offset:1024
	global_load_dwordx4 v[120:123], v[42:43], off offset:2048
	global_load_dwordx4 v[124:127], v[42:43], off offset:3072
	global_load_dwordx4 v[128:131], v[26:27], off
	global_load_dwordx4 v[132:135], v[26:27], off offset:1024
	global_load_dwordx4 v[136:139], v[26:27], off offset:2048
	global_load_dwordx4 v[140:143], v[26:27], off offset:3072
	s_waitcnt vmcnt(15)
	v_lshlrev_b32_e32 v48, 16, v80
	v_and_b32_e32 v49, 0xffff0000, v80
	v_lshlrev_b32_e32 v50, 16, v81
	v_and_b32_e32 v51, 0xffff0000, v81
	v_lshlrev_b32_e32 v52, 16, v82
	v_and_b32_e32 v53, 0xffff0000, v82
	v_lshlrev_b32_e32 v54, 16, v83
	v_and_b32_e32 v55, 0xffff0000, v83
	s_waitcnt vmcnt(14)
	v_lshlrev_b32_e32 v60, 16, v84
	v_and_b32_e32 v61, 0xffff0000, v84
	v_lshlrev_b32_e32 v56, 16, v85
	v_and_b32_e32 v57, 0xffff0000, v85
	v_lshlrev_b32_e32 v62, 16, v86
	v_and_b32_e32 v63, 0xffff0000, v86
	v_lshlrev_b32_e32 v58, 16, v87
	v_and_b32_e32 v59, 0xffff0000, v87
	v_pk_mul_f32 v[48:49], v[16:17], v[48:49] op_sel_hi:[0,1]
	v_pk_mul_f32 v[50:51], v[16:17], v[50:51] op_sel_hi:[0,1]
	v_pk_mul_f32 v[52:53], v[16:17], v[52:53] op_sel_hi:[0,1]
	v_pk_mul_f32 v[54:55], v[16:17], v[54:55] op_sel_hi:[0,1]
	v_pk_mul_f32 v[60:61], v[16:17], v[60:61] op_sel_hi:[0,1]
	v_pk_mul_f32 v[56:57], v[16:17], v[56:57] op_sel_hi:[0,1]
	v_pk_mul_f32 v[74:75], v[16:17], v[62:63] op_sel_hi:[0,1]
	v_pk_mul_f32 v[16:17], v[16:17], v[58:59] op_sel_hi:[0,1]
	v_pk_mul_f32 v[50:51], v[6:7], v[50:51]
	v_pk_mul_f32 v[48:49], v[4:5], v[48:49]
	v_pk_mul_f32 v[54:55], v[2:3], v[54:55]
	v_pk_mul_f32 v[52:53], v[0:1], v[52:53]
	v_pk_mul_f32 v[58:59], v[14:15], v[56:57]
	v_pk_mul_f32 v[56:57], v[12:13], v[60:61]
	v_pk_mul_f32 v[62:63], v[10:11], v[16:17]
	v_pk_mul_f32 v[60:61], v[8:9], v[74:75]
	global_store_dwordx4 v[24:25], v[48:51], off
	global_store_dwordx4 v[24:25], v[52:55], off offset:16
	global_store_dwordx4 v[24:25], v[56:59], off offset:2048
	global_store_dwordx4 v[24:25], v[60:63], off offset:2064
	s_nop 0
	s_add_u32 s10, s10, 0x4000
	s_addc_u32 s11, s11, 0
	s_cmp_lg_u32 s12, 0x20000
	s_waitcnt vmcnt(17)
	v_lshlrev_b32_e32 v16, 16, v88
	v_and_b32_e32 v17, 0xffff0000, v88
	v_lshlrev_b32_e32 v28, 16, v89
	v_and_b32_e32 v29, 0xffff0000, v89
	v_lshlrev_b32_e32 v48, 16, v90
	v_and_b32_e32 v49, 0xffff0000, v90
	v_lshlrev_b32_e32 v50, 16, v91
	v_and_b32_e32 v51, 0xffff0000, v91
	s_waitcnt vmcnt(16)
	v_lshlrev_b32_e32 v56, 16, v92
	v_and_b32_e32 v57, 0xffff0000, v92
	v_lshlrev_b32_e32 v52, 16, v93
	v_and_b32_e32 v53, 0xffff0000, v93
	v_lshlrev_b32_e32 v58, 16, v94
	v_and_b32_e32 v59, 0xffff0000, v94
	v_lshlrev_b32_e32 v54, 16, v95
	v_and_b32_e32 v55, 0xffff0000, v95
	v_pk_mul_f32 v[16:17], v[32:33], v[16:17] op_sel_hi:[0,1]
	v_pk_mul_f32 v[28:29], v[32:33], v[28:29] op_sel_hi:[0,1]
	v_pk_mul_f32 v[60:61], v[32:33], v[48:49] op_sel_hi:[0,1]
	v_pk_mul_f32 v[62:63], v[32:33], v[50:51] op_sel_hi:[0,1]
	v_pk_mul_f32 v[56:57], v[32:33], v[56:57] op_sel_hi:[0,1]
	v_pk_mul_f32 v[74:75], v[32:33], v[52:53] op_sel_hi:[0,1]
	v_pk_mul_f32 v[76:77], v[32:33], v[58:59] op_sel_hi:[0,1]
	v_pk_mul_f32 v[32:33], v[32:33], v[54:55] op_sel_hi:[0,1]
	v_pk_mul_f32 v[50:51], v[6:7], v[28:29]
	v_pk_mul_f32 v[48:49], v[4:5], v[16:17]
	v_pk_mul_f32 v[54:55], v[2:3], v[62:63]
	v_pk_mul_f32 v[52:53], v[0:1], v[60:61]
	v_pk_mul_f32 v[58:59], v[14:15], v[74:75]
	v_pk_mul_f32 v[56:57], v[12:13], v[56:57]
	v_pk_mul_f32 v[62:63], v[10:11], v[32:33]
	v_pk_mul_f32 v[60:61], v[8:9], v[76:77]
	global_store_dwordx4 v[30:31], v[48:51], off offset:-4096
	global_store_dwordx4 v[34:35], v[52:55], off offset:16
	global_store_dwordx4 v[34:35], v[56:59], off offset:2048
	global_store_dwordx4 v[34:35], v[60:63], off offset:2064
	s_nop 0
	s_waitcnt vmcnt(19)
	v_lshlrev_b32_e32 v16, 16, v96
	v_and_b32_e32 v17, 0xffff0000, v96
	v_lshlrev_b32_e32 v28, 16, v97
	v_and_b32_e32 v29, 0xffff0000, v97
	v_lshlrev_b32_e32 v32, 16, v98
	v_and_b32_e32 v33, 0xffff0000, v98
	v_lshlrev_b32_e32 v34, 16, v99
	v_and_b32_e32 v35, 0xffff0000, v99
	s_waitcnt vmcnt(18)
	v_lshlrev_b32_e32 v52, 16, v100
	v_and_b32_e32 v53, 0xffff0000, v100
	v_lshlrev_b32_e32 v48, 16, v101
	v_and_b32_e32 v49, 0xffff0000, v101
	v_lshlrev_b32_e32 v54, 16, v102
	v_and_b32_e32 v55, 0xffff0000, v102
	v_lshlrev_b32_e32 v50, 16, v103
	v_and_b32_e32 v51, 0xffff0000, v103
	v_pk_mul_f32 v[16:17], v[66:67], v[16:17] op_sel_hi:[0,1]
	v_pk_mul_f32 v[28:29], v[66:67], v[28:29] op_sel_hi:[0,1]
	v_pk_mul_f32 v[56:57], v[66:67], v[32:33] op_sel_hi:[0,1]
	v_pk_mul_f32 v[58:59], v[66:67], v[34:35] op_sel_hi:[0,1]
	v_pk_mul_f32 v[52:53], v[66:67], v[52:53] op_sel_hi:[0,1]
	v_pk_mul_f32 v[60:61], v[66:67], v[48:49] op_sel_hi:[0,1]
	v_pk_mul_f32 v[62:63], v[66:67], v[54:55] op_sel_hi:[0,1]
	v_pk_mul_f32 v[66:67], v[66:67], v[50:51] op_sel_hi:[0,1]
	v_pk_mul_f32 v[34:35], v[6:7], v[28:29]
	v_pk_mul_f32 v[32:33], v[4:5], v[16:17]
	v_pk_mul_f32 v[50:51], v[2:3], v[58:59]
	v_pk_mul_f32 v[48:49], v[0:1], v[56:57]
	v_pk_mul_f32 v[54:55], v[14:15], v[60:61]
	v_pk_mul_f32 v[52:53], v[12:13], v[52:53]
	v_pk_mul_f32 v[58:59], v[10:11], v[66:67]
	v_pk_mul_f32 v[56:57], v[8:9], v[62:63]
	global_store_dwordx4 v[30:31], v[32:35], off
	global_store_dwordx4 v[30:31], v[48:51], off offset:16
	global_store_dwordx4 v[30:31], v[52:55], off offset:2048
	global_store_dwordx4 v[30:31], v[56:59], off offset:2064
	s_nop 0
	s_waitcnt vmcnt(21)
	v_lshlrev_b32_e32 v16, 16, v104
	v_and_b32_e32 v17, 0xffff0000, v104
	v_lshlrev_b32_e32 v28, 16, v105
	v_and_b32_e32 v29, 0xffff0000, v105
	v_lshlrev_b32_e32 v48, 16, v106
	v_and_b32_e32 v49, 0xffff0000, v106
	v_lshlrev_b32_e32 v30, 16, v107
	v_and_b32_e32 v31, 0xffff0000, v107
	s_waitcnt vmcnt(20)
	v_lshlrev_b32_e32 v50, 16, v108
	v_and_b32_e32 v51, 0xffff0000, v108
	v_lshlrev_b32_e32 v32, 16, v109
	v_and_b32_e32 v33, 0xffff0000, v109
	v_lshlrev_b32_e32 v52, 16, v110
	v_and_b32_e32 v53, 0xffff0000, v110
	v_lshlrev_b32_e32 v34, 16, v111
	v_and_b32_e32 v35, 0xffff0000, v111
	v_pk_mul_f32 v[16:17], v[68:69], v[16:17] op_sel_hi:[0,1]
	v_pk_mul_f32 v[28:29], v[68:69], v[28:29] op_sel_hi:[0,1]
	v_pk_mul_f32 v[48:49], v[68:69], v[48:49] op_sel_hi:[0,1]
	v_pk_mul_f32 v[54:55], v[68:69], v[30:31] op_sel_hi:[0,1]
	v_pk_mul_f32 v[56:57], v[68:69], v[50:51] op_sel_hi:[0,1]
	v_pk_mul_f32 v[50:51], v[68:69], v[32:33] op_sel_hi:[0,1]
	v_pk_mul_f32 v[52:53], v[68:69], v[52:53] op_sel_hi:[0,1]
	v_pk_mul_f32 v[58:59], v[68:69], v[34:35] op_sel_hi:[0,1]
	v_pk_mul_f32 v[30:31], v[6:7], v[28:29]
	v_pk_mul_f32 v[28:29], v[4:5], v[16:17]
	v_pk_mul_f32 v[34:35], v[2:3], v[54:55]
	v_pk_mul_f32 v[32:33], v[0:1], v[48:49]
	v_pk_mul_f32 v[50:51], v[14:15], v[50:51]
	v_pk_mul_f32 v[48:49], v[12:13], v[56:57]
	v_pk_mul_f32 v[54:55], v[10:11], v[58:59]
	v_pk_mul_f32 v[52:53], v[8:9], v[52:53]
	global_store_dwordx4 v[36:37], v[28:31], off offset:-4096
	global_store_dwordx4 v[40:41], v[32:35], off offset:16
	global_store_dwordx4 v[40:41], v[48:51], off offset:2048
	global_store_dwordx4 v[40:41], v[52:55], off offset:2064
	s_nop 0
	s_waitcnt vmcnt(23)
	v_lshlrev_b32_e32 v16, 16, v112
	v_and_b32_e32 v17, 0xffff0000, v112
	v_lshlrev_b32_e32 v28, 16, v113
	v_and_b32_e32 v29, 0xffff0000, v113
	v_lshlrev_b32_e32 v40, 16, v114
	v_and_b32_e32 v41, 0xffff0000, v114
	v_lshlrev_b32_e32 v30, 16, v115
	v_and_b32_e32 v31, 0xffff0000, v115
	s_waitcnt vmcnt(22)
	v_lshlrev_b32_e32 v48, 16, v116
	v_and_b32_e32 v49, 0xffff0000, v116
	v_lshlrev_b32_e32 v32, 16, v117
	v_and_b32_e32 v33, 0xffff0000, v117
	v_lshlrev_b32_e32 v50, 16, v118
	v_and_b32_e32 v51, 0xffff0000, v118
	v_lshlrev_b32_e32 v34, 16, v119
	v_and_b32_e32 v35, 0xffff0000, v119
	v_pk_mul_f32 v[16:17], v[70:71], v[16:17] op_sel_hi:[0,1]
	v_pk_mul_f32 v[28:29], v[70:71], v[28:29] op_sel_hi:[0,1]
	v_pk_mul_f32 v[40:41], v[70:71], v[40:41] op_sel_hi:[0,1]
	v_pk_mul_f32 v[52:53], v[70:71], v[30:31] op_sel_hi:[0,1]
	v_pk_mul_f32 v[48:49], v[70:71], v[48:49] op_sel_hi:[0,1]
	v_pk_mul_f32 v[54:55], v[70:71], v[32:33] op_sel_hi:[0,1]
	v_pk_mul_f32 v[56:57], v[70:71], v[50:51] op_sel_hi:[0,1]
	v_pk_mul_f32 v[58:59], v[70:71], v[34:35] op_sel_hi:[0,1]
	v_pk_mul_f32 v[30:31], v[6:7], v[28:29]
	v_pk_mul_f32 v[28:29], v[4:5], v[16:17]
	v_pk_mul_f32 v[34:35], v[2:3], v[52:53]
	v_pk_mul_f32 v[32:33], v[0:1], v[40:41]
	v_pk_mul_f32 v[50:51], v[14:15], v[54:55]
	v_pk_mul_f32 v[48:49], v[12:13], v[48:49]
	v_pk_mul_f32 v[54:55], v[10:11], v[58:59]
	v_pk_mul_f32 v[52:53], v[8:9], v[56:57]
	global_store_dwordx4 v[36:37], v[28:31], off
	global_store_dwordx4 v[36:37], v[32:35], off offset:16
	global_store_dwordx4 v[36:37], v[48:51], off offset:2048
	global_store_dwordx4 v[36:37], v[52:55], off offset:2064
	s_nop 0
	s_waitcnt vmcnt(25)
	v_lshlrev_b32_e32 v16, 16, v120
	v_and_b32_e32 v17, 0xffff0000, v120
	v_lshlrev_b32_e32 v28, 16, v121
	v_and_b32_e32 v29, 0xffff0000, v121
	v_lshlrev_b32_e32 v36, 16, v122
	v_and_b32_e32 v37, 0xffff0000, v122
	v_lshlrev_b32_e32 v30, 16, v123
	v_and_b32_e32 v31, 0xffff0000, v123
	s_waitcnt vmcnt(24)
	v_lshlrev_b32_e32 v40, 16, v124
	v_and_b32_e32 v41, 0xffff0000, v124
	v_lshlrev_b32_e32 v32, 16, v125
	v_and_b32_e32 v33, 0xffff0000, v125
	v_lshlrev_b32_e32 v42, 16, v126
	v_and_b32_e32 v43, 0xffff0000, v126
	v_lshlrev_b32_e32 v34, 16, v127
	v_and_b32_e32 v35, 0xffff0000, v127
	v_pk_mul_f32 v[16:17], v[72:73], v[16:17] op_sel_hi:[0,1]
	v_pk_mul_f32 v[28:29], v[72:73], v[28:29] op_sel_hi:[0,1]
	v_pk_mul_f32 v[36:37], v[72:73], v[36:37] op_sel_hi:[0,1]
	v_pk_mul_f32 v[48:49], v[72:73], v[30:31] op_sel_hi:[0,1]
	v_pk_mul_f32 v[40:41], v[72:73], v[40:41] op_sel_hi:[0,1]
	v_pk_mul_f32 v[50:51], v[72:73], v[32:33] op_sel_hi:[0,1]
	v_pk_mul_f32 v[52:53], v[72:73], v[42:43] op_sel_hi:[0,1]
	v_pk_mul_f32 v[54:55], v[72:73], v[34:35] op_sel_hi:[0,1]
	v_pk_mul_f32 v[30:31], v[6:7], v[28:29]
	v_pk_mul_f32 v[28:29], v[4:5], v[16:17]
	v_pk_mul_f32 v[34:35], v[2:3], v[48:49]
	v_pk_mul_f32 v[32:33], v[0:1], v[36:37]
	v_pk_mul_f32 v[42:43], v[14:15], v[50:51]
	v_pk_mul_f32 v[40:41], v[12:13], v[40:41]
	v_pk_mul_f32 v[50:51], v[10:11], v[54:55]
	v_pk_mul_f32 v[48:49], v[8:9], v[52:53]
	global_store_dwordx4 v[38:39], v[28:31], off offset:-4096
	global_store_dwordx4 v[44:45], v[32:35], off offset:16
	global_store_dwordx4 v[44:45], v[40:43], off offset:2048
	global_store_dwordx4 v[44:45], v[48:51], off offset:2064
	s_nop 0
	v_fmamk_f32 v16, v18, 0x3a800000, v46
	v_mul_f32_e32 v17, 0x4b800000, v16
	v_cmp_gt_f32_e32 vcc, s15, v16
	s_waitcnt vmcnt(27)
	v_lshlrev_b32_e32 v36, 16, v128
	v_cndmask_b32_e32 v16, v16, v17, vcc
	v_rsq_f32_e32 v16, v16
	v_and_b32_e32 v37, 0xffff0000, v128
	v_lshlrev_b32_e32 v28, 16, v129
	v_and_b32_e32 v29, 0xffff0000, v129
	v_mul_f32_e32 v17, 0x45800000, v16
	v_cndmask_b32_e32 v16, v16, v17, vcc
	v_lshlrev_b32_e32 v40, 16, v130
	v_and_b32_e32 v41, 0xffff0000, v130
	v_lshlrev_b32_e32 v30, 16, v131
	v_and_b32_e32 v31, 0xffff0000, v131
	s_waitcnt vmcnt(26)
	v_lshlrev_b32_e32 v42, 16, v132
	v_and_b32_e32 v43, 0xffff0000, v132
	v_lshlrev_b32_e32 v32, 16, v133
	v_and_b32_e32 v33, 0xffff0000, v133
	v_lshlrev_b32_e32 v44, 16, v134
	v_and_b32_e32 v45, 0xffff0000, v134
	v_lshlrev_b32_e32 v34, 16, v135
	v_and_b32_e32 v35, 0xffff0000, v135
	v_pk_mul_f32 v[36:37], v[16:17], v[36:37] op_sel_hi:[0,1]
	v_pk_mul_f32 v[28:29], v[16:17], v[28:29] op_sel_hi:[0,1]
	v_pk_mul_f32 v[40:41], v[16:17], v[40:41] op_sel_hi:[0,1]
	v_pk_mul_f32 v[48:49], v[16:17], v[30:31] op_sel_hi:[0,1]
	v_pk_mul_f32 v[50:51], v[16:17], v[42:43] op_sel_hi:[0,1]
	v_pk_mul_f32 v[42:43], v[16:17], v[32:33] op_sel_hi:[0,1]
	v_pk_mul_f32 v[44:45], v[16:17], v[44:45] op_sel_hi:[0,1]
	v_pk_mul_f32 v[16:17], v[16:17], v[34:35] op_sel_hi:[0,1]
	v_pk_mul_f32 v[30:31], v[6:7], v[28:29]
	v_pk_mul_f32 v[28:29], v[4:5], v[36:37]
	v_pk_mul_f32 v[34:35], v[2:3], v[48:49]
	v_pk_mul_f32 v[32:33], v[0:1], v[40:41]
	v_pk_mul_f32 v[42:43], v[14:15], v[42:43]
	v_pk_mul_f32 v[40:41], v[12:13], v[50:51]
	v_pk_mul_f32 v[50:51], v[10:11], v[16:17]
	v_pk_mul_f32 v[48:49], v[8:9], v[44:45]
	global_store_dwordx4 v[38:39], v[28:31], off
	global_store_dwordx4 v[38:39], v[32:35], off offset:16
	global_store_dwordx4 v[38:39], v[40:43], off offset:2048
	global_store_dwordx4 v[38:39], v[48:51], off offset:2064
	s_nop 0
	v_add_co_u32_e32 v36, vcc, s26, v24
	v_fmamk_f32 v16, v19, 0x3a800000, v46
	s_nop 0
	v_addc_co_u32_e32 v37, vcc, 0, v25, vcc
	v_mul_f32_e32 v17, 0x4b800000, v16
	v_cmp_gt_f32_e32 vcc, s15, v16
	s_waitcnt vmcnt(29)
	v_lshlrev_b32_e32 v18, 16, v136
	v_cndmask_b32_e32 v16, v16, v17, vcc
	v_rsq_f32_e32 v16, v16
	v_and_b32_e32 v19, 0xffff0000, v136
	v_lshlrev_b32_e32 v24, 16, v137
	v_and_b32_e32 v25, 0xffff0000, v137
	v_mul_f32_e32 v17, 0x45800000, v16
	v_cndmask_b32_e32 v16, v16, v17, vcc
	v_lshlrev_b32_e32 v26, 16, v138
	v_and_b32_e32 v27, 0xffff0000, v138
	v_lshlrev_b32_e32 v28, 16, v139
	v_and_b32_e32 v29, 0xffff0000, v139
	s_waitcnt vmcnt(28)
	v_lshlrev_b32_e32 v30, 16, v140
	v_and_b32_e32 v31, 0xffff0000, v140
	v_lshlrev_b32_e32 v32, 16, v141
	v_and_b32_e32 v33, 0xffff0000, v141
	v_lshlrev_b32_e32 v38, 16, v142
	v_and_b32_e32 v39, 0xffff0000, v142
	v_lshlrev_b32_e32 v34, 16, v143
	v_and_b32_e32 v35, 0xffff0000, v143
	v_pk_mul_f32 v[40:41], v[16:17], v[18:19] op_sel_hi:[0,1]
	v_pk_mul_f32 v[18:19], v[16:17], v[24:25] op_sel_hi:[0,1]
	v_pk_mul_f32 v[24:25], v[16:17], v[26:27] op_sel_hi:[0,1]
	v_pk_mul_f32 v[26:27], v[16:17], v[28:29] op_sel_hi:[0,1]
	v_pk_mul_f32 v[28:29], v[16:17], v[30:31] op_sel_hi:[0,1]
	v_pk_mul_f32 v[30:31], v[16:17], v[32:33] op_sel_hi:[0,1]
	v_pk_mul_f32 v[32:33], v[16:17], v[38:39] op_sel_hi:[0,1]
	v_pk_mul_f32 v[34:35], v[16:17], v[34:35] op_sel_hi:[0,1]
	v_pk_mul_f32 v[18:19], v[6:7], v[18:19]
	v_pk_mul_f32 v[16:17], v[4:5], v[40:41]
	v_pk_mul_f32 v[26:27], v[2:3], v[26:27]
	v_pk_mul_f32 v[24:25], v[0:1], v[24:25]
	v_pk_mul_f32 v[30:31], v[14:15], v[30:31]
	v_pk_mul_f32 v[28:29], v[12:13], v[28:29]
	v_pk_mul_f32 v[34:35], v[10:11], v[34:35]
	v_pk_mul_f32 v[32:33], v[8:9], v[32:33]
	global_store_dwordx4 v[36:37], v[16:19], off
	global_store_dwordx4 v[36:37], v[24:27], off offset:16
	global_store_dwordx4 v[36:37], v[28:31], off offset:2048
	global_store_dwordx4 v[36:37], v[32:35], off offset:2064
	s_cbranch_scc1 .LBB0_582
	s_endpgm
